# v10-plus-H-stores-sc1
# speedup vs baseline: 1.0038x; 1.0038x over previous
; __device__ __forceinline__ unsigned cvt_pk_bf16(float lo, float hi) { f32x2_cv v = {lo, hi}; bf16x2_cv b = __builtin_convertvector(v, bf16x2_cv); return __builtin_bit_cast(unsigned, b); }
;     __device__ __forceinline__ void operator()(const f32x4 (&acc)[2][2][4][2], const Unit& u, int wr, int wc, int fr, int fq) const {
;     ...
;                     for (int j = 0; j < 2; ++j) { const f32x4 ga = acc[ai][0][m][n], ua = acc[ai][1][m][n];
;                         f32x2 g = (f32x2){ga[2 * j], ga[2 * j + 1]}, up = (f32x2){ua[2 * j], ua[2 * j + 1]};
;                         if constexpr (!FUSE) { g = g * r; up = up * r; }
;                         const f32x2 t = g; f32x2 e; e.x = __builtin_amdgcn_exp2f(t.x); e.y = __builtin_amdgcn_exp2f(t.y);
;                         const f32x2 d = e + 1.0f; f32x2 q; q.x = __builtin_amdgcn_rcpf(d.x); q.y = __builtin_amdgcn_rcpf(d.y);
;                         hv[n * 2 + j] = (g * q) * up; }
;                 u32x4 w; w.x = cvt_pk_bf16(hv[0].x, hv[0].y); w.y = cvt_pk_bf16(hv[1].x, hv[1].y); w.z = cvt_pk_bf16(hv[2].x, hv[2].y); w.w = cvt_pk_bf16(hv[3].x, hv[3].y);
;                 *(u32x4*)(H + (unsigned)(row * P_DFF + col0)) = w; }
.LBB0_812:
	v_exp_f32_e32 v132, v128
	v_exp_f32_e32 v133, v129
	v_exp_f32_e32 v134, v122
	v_exp_f32_e32 v135, v123
	v_exp_f32_e32 v138, v124
	v_exp_f32_e32 v139, v125
	v_pk_add_f32 v[132:133], v[132:133], 1.0 op_sel_hi:[1,0]
	v_pk_add_f32 v[134:135], v[134:135], 1.0 op_sel_hi:[1,0]
	v_rcp_f32_e32 v132, v132
	v_rcp_f32_e32 v133, v133
	v_exp_f32_e32 v130, v126
	v_exp_f32_e32 v131, v127
	v_rcp_f32_e32 v134, v134
	v_rcp_f32_e32 v135, v135
	v_pk_add_f32 v[138:139], v[138:139], 1.0 op_sel_hi:[1,0]
	v_pk_mul_f32 v[132:133], v[128:129], v[132:133]
	v_rcp_f32_e32 v138, v138
	v_rcp_f32_e32 v139, v139
	v_pk_add_f32 v[130:131], v[130:131], 1.0 op_sel_hi:[1,0]
	v_pk_mul_f32 v[140:141], v[132:133], v[96:97]
	v_pk_mul_f32 v[132:133], v[122:123], v[134:135]
	v_rcp_f32_e32 v130, v130
	v_rcp_f32_e32 v131, v131
	v_pk_mul_f32 v[134:135], v[132:133], v[90:91]
	v_pk_mul_f32 v[132:133], v[124:125], v[138:139]
	v_cvt_pk_bf16_f32 v134, v134, v135
	v_pk_mul_f32 v[138:139], v[132:133], v[92:93]
	v_pk_mul_f32 v[130:131], v[126:127], v[130:131]
	v_cvt_pk_bf16_f32 v135, v138, v139
	v_exp_f32_e32 v138, v118
	v_exp_f32_e32 v139, v119
	v_lshl_add_u32 v137, s22, 8, v209
	v_lshl_or_b32 v136, s70, 7, v206
	v_pk_mul_f32 v[130:131], v[130:131], v[94:95]
	v_cvt_pk_bf16_f32 v133, v140, v141
	v_cvt_pk_bf16_f32 v132, v130, v131
	v_mad_u64_u32 v[130:131], s[36:37], v137, s69, v[136:137]
	v_pk_add_f32 v[136:137], v[138:139], 1.0 op_sel_hi:[1,0]
	v_mov_b32_e32 v131, v197
	v_rcp_f32_e32 v136, v136
	v_rcp_f32_e32 v137, v137
	v_lshl_add_u64 v[140:141], v[130:131], 1, s[28:29]
	v_exp_f32_e32 v138, v120
	v_exp_f32_e32 v139, v121
	global_store_dwordx4 v[140:141], v[132:135], off sc1
	v_exp_f32_e32 v140, v110
	v_exp_f32_e32 v141, v111
	v_pk_mul_f32 v[132:133], v[118:119], v[136:137]
	v_exp_f32_e32 v136, v114
	v_exp_f32_e32 v137, v115
	v_pk_add_f32 v[134:135], v[138:139], 1.0 op_sel_hi:[1,0]
	v_exp_f32_e32 v138, v116
	v_exp_f32_e32 v139, v117
	v_pk_add_f32 v[136:137], v[136:137], 1.0 op_sel_hi:[1,0]
	v_rcp_f32_e32 v134, v134
	v_rcp_f32_e32 v135, v135
	v_rcp_f32_e32 v136, v136
	v_rcp_f32_e32 v137, v137
	v_pk_add_f32 v[138:139], v[138:139], 1.0 op_sel_hi:[1,0]
	v_pk_mul_f32 v[134:135], v[120:121], v[134:135]
	v_rcp_f32_e32 v138, v138
	v_rcp_f32_e32 v139, v139
	v_pk_mul_f32 v[136:137], v[114:115], v[136:137]
	v_pk_mul_f32 v[132:133], v[132:133], v[86:87]
	v_pk_mul_f32 v[134:135], v[134:135], v[88:89]
	v_pk_mul_f32 v[136:137], v[136:137], v[82:83]
	v_cvt_pk_bf16_f32 v132, v132, v133
	v_cvt_pk_bf16_f32 v133, v134, v135
	v_cvt_pk_bf16_f32 v134, v136, v137
	v_pk_add_f32 v[136:137], v[140:141], 1.0 op_sel_hi:[1,0]
	v_pk_mul_f32 v[138:139], v[116:117], v[138:139]
	v_rcp_f32_e32 v136, v136
	v_rcp_f32_e32 v137, v137
	v_pk_mul_f32 v[138:139], v[138:139], v[84:85]
	v_add_u32_e32 v196, 0x16000, v130
	v_cvt_pk_bf16_f32 v135, v138, v139
	v_lshl_add_u64 v[140:141], v[196:197], 1, s[28:29]
	v_exp_f32_e32 v138, v112
	v_exp_f32_e32 v139, v113
	global_store_dwordx4 v[140:141], v[132:135], off sc1
	v_exp_f32_e32 v140, v102
	v_exp_f32_e32 v141, v103
	v_pk_mul_f32 v[132:133], v[110:111], v[136:137]
	v_exp_f32_e32 v136, v106
	v_exp_f32_e32 v137, v107
	v_pk_add_f32 v[134:135], v[138:139], 1.0 op_sel_hi:[1,0]
	v_exp_f32_e32 v138, v108
	v_exp_f32_e32 v139, v109
	v_pk_add_f32 v[136:137], v[136:137], 1.0 op_sel_hi:[1,0]
	v_rcp_f32_e32 v134, v134
	v_rcp_f32_e32 v135, v135
	v_rcp_f32_e32 v136, v136
	v_rcp_f32_e32 v137, v137
	v_pk_add_f32 v[138:139], v[138:139], 1.0 op_sel_hi:[1,0]
	v_pk_mul_f32 v[134:135], v[112:113], v[134:135]
	v_rcp_f32_e32 v138, v138
	v_rcp_f32_e32 v139, v139
	v_pk_mul_f32 v[136:137], v[106:107], v[136:137]
	v_pk_mul_f32 v[132:133], v[132:133], v[78:79]
	v_pk_mul_f32 v[134:135], v[134:135], v[80:81]
	v_pk_mul_f32 v[136:137], v[136:137], v[74:75]
	v_cvt_pk_bf16_f32 v132, v132, v133
	v_cvt_pk_bf16_f32 v133, v134, v135
	v_cvt_pk_bf16_f32 v134, v136, v137
	v_pk_add_f32 v[136:137], v[140:141], 1.0 op_sel_hi:[1,0]
	v_pk_mul_f32 v[138:139], v[108:109], v[138:139]
	v_rcp_f32_e32 v136, v136
	v_rcp_f32_e32 v137, v137
	v_pk_mul_f32 v[138:139], v[138:139], v[76:77]
	v_add_u32_e32 v196, 0x2c000, v130
	v_cvt_pk_bf16_f32 v135, v138, v139
	v_lshl_add_u64 v[140:141], v[196:197], 1, s[28:29]
	v_exp_f32_e32 v138, v104
	v_exp_f32_e32 v139, v105
	global_store_dwordx4 v[140:141], v[132:135], off sc1
	v_exp_f32_e32 v140, v62
	v_exp_f32_e32 v141, v63
	v_pk_mul_f32 v[132:133], v[102:103], v[136:137]
	v_exp_f32_e32 v136, v98
	v_exp_f32_e32 v137, v99
	v_pk_add_f32 v[134:135], v[138:139], 1.0 op_sel_hi:[1,0]
	v_exp_f32_e32 v138, v100
	v_exp_f32_e32 v139, v101
	v_pk_add_f32 v[136:137], v[136:137], 1.0 op_sel_hi:[1,0]
	v_rcp_f32_e32 v134, v134
	v_rcp_f32_e32 v135, v135
	v_rcp_f32_e32 v136, v136
	v_rcp_f32_e32 v137, v137
	v_pk_add_f32 v[138:139], v[138:139], 1.0 op_sel_hi:[1,0]
	v_pk_mul_f32 v[134:135], v[104:105], v[134:135]
	v_rcp_f32_e32 v138, v138
	v_rcp_f32_e32 v139, v139
	v_pk_mul_f32 v[136:137], v[98:99], v[136:137]
	v_pk_mul_f32 v[132:133], v[132:133], v[70:71]
	v_pk_mul_f32 v[134:135], v[134:135], v[72:73]
	v_pk_mul_f32 v[136:137], v[136:137], v[66:67]
	v_cvt_pk_bf16_f32 v132, v132, v133
	v_cvt_pk_bf16_f32 v133, v134, v135
	v_cvt_pk_bf16_f32 v134, v136, v137
	v_pk_add_f32 v[136:137], v[140:141], 1.0 op_sel_hi:[1,0]
	v_pk_mul_f32 v[138:139], v[100:101], v[138:139]
	v_rcp_f32_e32 v136, v136
	v_rcp_f32_e32 v137, v137
	v_pk_mul_f32 v[138:139], v[138:139], v[68:69]
; __device__ __forceinline__ unsigned cvt_pk_bf16(float lo, float hi) { f32x2_cv v = {lo, hi}; bf16x2_cv b = __builtin_convertvector(v, bf16x2_cv); return __builtin_bit_cast(unsigned, b); }
; #define PG8_BAR __builtin_amdgcn_s_barrier()
;     __device__ __forceinline__ void operator()(const f32x4 (&acc)[2][2][4][2], const Unit& u, int wr, int wc, int fr, int fq) const {
;     ...
;                     for (int j = 0; j < 2; ++j) { const f32x4 ga = acc[ai][0][m][n], ua = acc[ai][1][m][n];
;                         f32x2 g = (f32x2){ga[2 * j], ga[2 * j + 1]}, up = (f32x2){ua[2 * j], ua[2 * j + 1]};
;                         if constexpr (!FUSE) { g = g * r; up = up * r; }
;                         const f32x2 t = g; f32x2 e; e.x = __builtin_amdgcn_exp2f(t.x); e.y = __builtin_amdgcn_exp2f(t.y);
;                         const f32x2 d = e + 1.0f; f32x2 q; q.x = __builtin_amdgcn_rcpf(d.x); q.y = __builtin_amdgcn_rcpf(d.y);
;                         hv[n * 2 + j] = (g * q) * up; }
;                 u32x4 w; w.x = cvt_pk_bf16(hv[0].x, hv[0].y); w.y = cvt_pk_bf16(hv[1].x, hv[1].y); w.z = cvt_pk_bf16(hv[2].x, hv[2].y); w.w = cvt_pk_bf16(hv[3].x, hv[3].y);
;                 *(u32x4*)(H + (unsigned)(row * P_DFF + col0)) = w; }
; template <class Epi, class Sched, bool ALIGN_EPI = false, bool SP2 = false>
; __device__ __forceinline__ void gemm_phase(PG8_LAS unsigned char* lds, const Gemm g, const Sched& S, const Epi& E) {
;     ...
;         if (!has_next) break;
;         cur = nxt; cA = nA; cB = nB; ++ui;
;         if constexpr (ALIGN_EPI) { if (wr == 1) PG8_BAR; }
	v_add_u32_e32 v196, 0x42000, v130
	v_cvt_pk_bf16_f32 v135, v138, v139
	v_exp_f32_e32 v138, v64
	v_exp_f32_e32 v139, v65
	v_lshl_add_u64 v[140:141], v[196:197], 1, s[28:29]
	global_store_dwordx4 v[140:141], v[132:135], off sc1
	v_exp_f32_e32 v140, v54
	v_exp_f32_e32 v141, v55
	v_pk_mul_f32 v[132:133], v[62:63], v[136:137]
	v_exp_f32_e32 v136, v58
	v_exp_f32_e32 v137, v59
	v_pk_add_f32 v[134:135], v[138:139], 1.0 op_sel_hi:[1,0]
	v_exp_f32_e32 v138, v60
	v_exp_f32_e32 v139, v61
	v_pk_add_f32 v[136:137], v[136:137], 1.0 op_sel_hi:[1,0]
	v_rcp_f32_e32 v134, v134
	v_rcp_f32_e32 v135, v135
	v_rcp_f32_e32 v136, v136
	v_rcp_f32_e32 v137, v137
	v_pk_add_f32 v[138:139], v[138:139], 1.0 op_sel_hi:[1,0]
	v_pk_mul_f32 v[134:135], v[64:65], v[134:135]
	v_rcp_f32_e32 v138, v138
	v_rcp_f32_e32 v139, v139
	v_pk_mul_f32 v[136:137], v[58:59], v[136:137]
	v_pk_mul_f32 v[132:133], v[132:133], v[30:31]
	v_pk_mul_f32 v[134:135], v[134:135], v[32:33]
	v_pk_mul_f32 v[136:137], v[136:137], v[26:27]
	v_cvt_pk_bf16_f32 v132, v132, v133
	v_cvt_pk_bf16_f32 v133, v134, v135
	v_cvt_pk_bf16_f32 v134, v136, v137
	v_pk_add_f32 v[136:137], v[140:141], 1.0 op_sel_hi:[1,0]
	v_pk_mul_f32 v[138:139], v[60:61], v[138:139]
	v_rcp_f32_e32 v136, v136
	v_rcp_f32_e32 v137, v137
	v_pk_mul_f32 v[138:139], v[138:139], v[28:29]
	v_add_u32_e32 v196, 0xb0000, v130
	v_cvt_pk_bf16_f32 v135, v138, v139
	v_exp_f32_e32 v138, v56
	v_exp_f32_e32 v139, v57
	v_lshl_add_u64 v[140:141], v[196:197], 1, s[28:29]
	global_store_dwordx4 v[140:141], v[132:135], off sc1
	v_exp_f32_e32 v140, v46
	v_exp_f32_e32 v141, v47
	v_pk_mul_f32 v[132:133], v[54:55], v[136:137]
	v_exp_f32_e32 v136, v50
	v_exp_f32_e32 v137, v51
	v_pk_add_f32 v[134:135], v[138:139], 1.0 op_sel_hi:[1,0]
	v_exp_f32_e32 v138, v52
	v_exp_f32_e32 v139, v53
	v_pk_add_f32 v[136:137], v[136:137], 1.0 op_sel_hi:[1,0]
	v_rcp_f32_e32 v134, v134
	v_rcp_f32_e32 v135, v135
	v_rcp_f32_e32 v136, v136
	v_rcp_f32_e32 v137, v137
	v_pk_add_f32 v[138:139], v[138:139], 1.0 op_sel_hi:[1,0]
	v_pk_mul_f32 v[134:135], v[56:57], v[134:135]
	v_rcp_f32_e32 v138, v138
	v_rcp_f32_e32 v139, v139
	v_pk_mul_f32 v[136:137], v[50:51], v[136:137]
	v_pk_mul_f32 v[132:133], v[132:133], v[22:23]
	v_pk_mul_f32 v[134:135], v[134:135], v[24:25]
	v_pk_mul_f32 v[136:137], v[136:137], v[18:19]
	v_pk_mul_f32 v[138:139], v[52:53], v[138:139]
	v_cvt_pk_bf16_f32 v132, v132, v133
	v_cvt_pk_bf16_f32 v133, v134, v135
	v_cvt_pk_bf16_f32 v134, v136, v137
	v_pk_add_f32 v[136:137], v[140:141], 1.0 op_sel_hi:[1,0]
	v_pk_mul_f32 v[138:139], v[138:139], v[20:21]
	v_rcp_f32_e32 v136, v136
	v_rcp_f32_e32 v137, v137
	v_cvt_pk_bf16_f32 v135, v138, v139
	v_exp_f32_e32 v138, v48
	v_exp_f32_e32 v139, v49
	v_add_u32_e32 v196, 0xc6000, v130
	v_lshl_add_u64 v[140:141], v[196:197], 1, s[28:29]
	global_store_dwordx4 v[140:141], v[132:135], off sc1
	v_exp_f32_e32 v140, v38
	v_exp_f32_e32 v141, v39
	v_pk_mul_f32 v[132:133], v[46:47], v[136:137]
	v_exp_f32_e32 v136, v42
	v_exp_f32_e32 v137, v43
	v_pk_add_f32 v[134:135], v[138:139], 1.0 op_sel_hi:[1,0]
	v_exp_f32_e32 v138, v44
	v_exp_f32_e32 v139, v45
	v_pk_add_f32 v[136:137], v[136:137], 1.0 op_sel_hi:[1,0]
	v_rcp_f32_e32 v134, v134
	v_rcp_f32_e32 v135, v135
	v_rcp_f32_e32 v136, v136
	v_rcp_f32_e32 v137, v137
	v_pk_add_f32 v[138:139], v[138:139], 1.0 op_sel_hi:[1,0]
	v_pk_mul_f32 v[134:135], v[48:49], v[134:135]
	v_rcp_f32_e32 v138, v138
	v_rcp_f32_e32 v139, v139
	v_pk_mul_f32 v[136:137], v[42:43], v[136:137]
	v_pk_mul_f32 v[132:133], v[132:133], v[14:15]
	v_pk_mul_f32 v[134:135], v[134:135], v[16:17]
	v_pk_mul_f32 v[136:137], v[136:137], v[10:11]
	v_pk_mul_f32 v[138:139], v[44:45], v[138:139]
	v_cvt_pk_bf16_f32 v132, v132, v133
	v_pk_mul_f32 v[138:139], v[138:139], v[12:13]
	v_cvt_pk_bf16_f32 v133, v134, v135
	v_cvt_pk_bf16_f32 v134, v136, v137
	v_pk_add_f32 v[136:137], v[140:141], 1.0 op_sel_hi:[1,0]
	v_cvt_pk_bf16_f32 v135, v138, v139
	v_rcp_f32_e32 v136, v136
	v_rcp_f32_e32 v137, v137
	v_exp_f32_e32 v138, v40
	v_exp_f32_e32 v139, v41
	v_add_u32_e32 v196, 0xdc000, v130
	v_lshl_add_u64 v[140:141], v[196:197], 1, s[28:29]
	global_store_dwordx4 v[140:141], v[132:135], off sc1
	v_add_u32_e32 v196, 0xf2000, v130
	v_lshl_add_u64 v[130:131], v[196:197], 1, s[28:29]
	v_pk_mul_f32 v[132:133], v[38:39], v[136:137]
	v_pk_add_f32 v[134:135], v[138:139], 1.0 op_sel_hi:[1,0]
	v_exp_f32_e32 v136, v34
	v_exp_f32_e32 v137, v35
	v_exp_f32_e32 v138, v36
	v_exp_f32_e32 v139, v37
	v_rcp_f32_e32 v134, v134
	v_pk_add_f32 v[136:137], v[136:137], 1.0 op_sel_hi:[1,0]
	v_rcp_f32_e32 v135, v135
	v_pk_add_f32 v[138:139], v[138:139], 1.0 op_sel_hi:[1,0]
	v_rcp_f32_e32 v136, v136
	v_rcp_f32_e32 v137, v137
	v_rcp_f32_e32 v138, v138
	v_rcp_f32_e32 v139, v139
	v_pk_mul_f32 v[134:135], v[40:41], v[134:135]
	v_pk_mul_f32 v[136:137], v[34:35], v[136:137]
	v_pk_mul_f32 v[132:133], v[132:133], v[6:7]
	v_pk_mul_f32 v[138:139], v[36:37], v[138:139]
	v_pk_mul_f32 v[134:135], v[134:135], v[8:9]
	v_pk_mul_f32 v[136:137], v[136:137], v[2:3]
	v_pk_mul_f32 v[138:139], v[138:139], v[4:5]
	v_cvt_pk_bf16_f32 v132, v132, v133
	v_cvt_pk_bf16_f32 v133, v134, v135
	v_cvt_pk_bf16_f32 v134, v136, v137
	v_cvt_pk_bf16_f32 v135, v138, v139
	s_andn2_b64 vcc, exec, s[0:1]
	s_mov_b64 s[0:1], -1
	global_store_dwordx4 v[130:131], v[132:135], off sc1
	s_cbranch_vccnz .LBB0_803
	s_andn2_b64 vcc, exec, s[2:3]
	s_cbranch_vccnz .LBB0_802
	s_barrier
	s_branch .LBB0_802
